# in-projection GEMM epilogues: the 64 '+0.0' packed adds per unit (bias-less EpiBf16) removed or turned into v_mov_b64 where they doubled as copies; s_nop added where a store's data registers are rewri
# baseline (speedup 1.0000x reference)
.LBB0_204:
	s_ashr_i32 s17, s44, 31
	s_lshr_b32 s17, s17, 30
	s_add_i32 s17, s44, s17
	s_ashr_i32 s24, s17, 2
	s_ashr_i32 s25, s24, 31
	s_lshl_b32 s13, s44, 8
	s_lshl_b64 s[28:29], s[24:25], 25
	s_add_u32 s28, s36, s28
	s_addc_u32 s29, s37, s29
	s_lshl_b32 s17, s24, 10
	s_sub_i32 s13, s13, s17
	v_lshl_add_u32 v156, s22, 8, v149
	v_or_b32_e32 v146, s13, v151
	v_ashrrev_i32_e32 v147, 31, v146
	v_ashrrev_i32_e32 v157, 31, v156
	v_lshl_add_u64 v[158:159], v[146:147], 1, s[28:29]
	v_lshlrev_b64 v[146:147], 11, v[156:157]
	v_lshl_add_u64 v[146:147], v[158:159], 0, v[146:147]
	v_mov_b64_e32 v[160:161], v[124:125]
	v_mov_b64_e32 v[124:125], v[122:123]
	v_cvt_pk_bf16_f32 v122, v126, v127
	v_cvt_pk_bf16_f32 v123, v128, v129
	v_cvt_pk_bf16_f32 v124, v124, v125
	v_cvt_pk_bf16_f32 v125, v160, v161
	global_store_dwordx4 v[146:147], v[122:125], off sc1
	s_nop 1
	v_mov_b64_e32 v[122:123], v[112:113]
	v_mov_b64_e32 v[112:113], v[110:111]
	v_cvt_pk_bf16_f32 v110, v118, v119
	v_cvt_pk_bf16_f32 v111, v120, v121
	v_cvt_pk_bf16_f32 v112, v112, v113
	v_cvt_pk_bf16_f32 v113, v122, v123
	global_store_dwordx4 v[146:147], v[110:113], off offset:256 sc1
	s_nop 1
	v_or_b32_e32 v110, 16, v156
	v_ashrrev_i32_e32 v111, 31, v110
	v_lshlrev_b64 v[110:111], 11, v[110:111]
	v_lshl_add_u64 v[110:111], v[158:159], 0, v[110:111]
	v_mov_b64_e32 v[112:113], v[116:117]
	v_mov_b64_e32 v[116:117], v[108:109]
	v_mov_b64_e32 v[108:109], v[106:107]
	v_cvt_pk_bf16_f32 v106, v114, v115
	v_cvt_pk_bf16_f32 v107, v112, v113
	v_cvt_pk_bf16_f32 v108, v108, v109
	v_cvt_pk_bf16_f32 v109, v116, v117
	global_store_dwordx4 v[110:111], v[106:109], off sc1
	s_nop 1
	v_mov_b64_e32 v[106:107], v[96:97]
	v_mov_b64_e32 v[96:97], v[94:95]
	v_cvt_pk_bf16_f32 v94, v102, v103
	v_cvt_pk_bf16_f32 v95, v104, v105
	v_cvt_pk_bf16_f32 v96, v96, v97
	v_cvt_pk_bf16_f32 v97, v106, v107
	global_store_dwordx4 v[110:111], v[94:97], off offset:256 sc1
	s_nop 1
	v_or_b32_e32 v94, 32, v156
	v_ashrrev_i32_e32 v95, 31, v94
	v_lshlrev_b64 v[94:95], 11, v[94:95]
	v_lshl_add_u64 v[94:95], v[158:159], 0, v[94:95]
	v_mov_b64_e32 v[96:97], v[100:101]
	v_mov_b64_e32 v[100:101], v[92:93]
	v_mov_b64_e32 v[92:93], v[90:91]
	v_cvt_pk_bf16_f32 v90, v98, v99
	v_cvt_pk_bf16_f32 v91, v96, v97
	s_mov_b32 s13, 0x40000
	v_cvt_pk_bf16_f32 v92, v92, v93
	v_cvt_pk_bf16_f32 v93, v100, v101
	global_store_dwordx4 v[94:95], v[90:93], off sc1
	s_nop 1
	s_mov_b64 s[24:25], 0x40000
	v_mov_b64_e32 v[90:91], v[80:81]
	v_mov_b64_e32 v[80:81], v[78:79]
	v_cvt_pk_bf16_f32 v78, v86, v87
	v_cvt_pk_bf16_f32 v79, v88, v89
	v_cvt_pk_bf16_f32 v80, v80, v81
	v_cvt_pk_bf16_f32 v81, v90, v91
	global_store_dwordx4 v[94:95], v[78:81], off offset:256 sc1
	s_nop 1
	v_or_b32_e32 v78, 48, v156
	v_ashrrev_i32_e32 v79, 31, v78
	v_lshlrev_b64 v[78:79], 11, v[78:79]
	v_lshl_add_u64 v[78:79], v[158:159], 0, v[78:79]
	v_mov_b64_e32 v[80:81], v[84:85]
	v_mov_b64_e32 v[84:85], v[76:77]
	v_mov_b64_e32 v[76:77], v[74:75]
	v_cvt_pk_bf16_f32 v74, v82, v83
	v_cvt_pk_bf16_f32 v75, v80, v81
	v_cvt_pk_bf16_f32 v76, v76, v77
	v_cvt_pk_bf16_f32 v77, v84, v85
	global_store_dwordx4 v[78:79], v[74:77], off sc1
	s_nop 1
	v_mov_b64_e32 v[74:75], v[68:69]
	v_mov_b64_e32 v[68:69], v[66:67]
	v_cvt_pk_bf16_f32 v66, v70, v71
	v_cvt_pk_bf16_f32 v67, v72, v73
	v_cvt_pk_bf16_f32 v68, v68, v69
	v_cvt_pk_bf16_f32 v69, v74, v75
	global_store_dwordx4 v[78:79], v[66:69], off offset:256 sc1
	s_nop 1
	v_mov_b64_e32 v[68:69], v[60:61]
	v_mov_b64_e32 v[60:61], v[58:59]
	v_cvt_pk_bf16_f32 v58, v62, v63
	v_add_co_u32_e32 v62, vcc, s13, v146
	v_cvt_pk_bf16_f32 v59, v64, v65
	v_cvt_pk_bf16_f32 v60, v60, v61
	v_cvt_pk_bf16_f32 v61, v68, v69
	v_lshl_add_u64 v[66:67], v[146:147], 0, s[24:25]
	s_nop 0
	v_addc_co_u32_e32 v63, vcc, 0, v147, vcc
	global_store_dwordx4 v[62:63], v[58:61], off sc1
	s_mov_b32 s13, 0x48000
	s_mov_b64 s[24:25], 0x48000
	v_mov_b64_e32 v[58:59], v[48:49]
	v_mov_b64_e32 v[48:49], v[46:47]
	v_cvt_pk_bf16_f32 v46, v54, v55
	v_cvt_pk_bf16_f32 v47, v56, v57
	v_cvt_pk_bf16_f32 v48, v48, v49
	v_cvt_pk_bf16_f32 v49, v58, v59
	global_store_dwordx4 v[66:67], v[46:49], off offset:256 sc1
	s_nop 1
	s_nop 0
	v_mov_b64_e32 v[48:49], v[52:53]
	v_mov_b64_e32 v[52:53], v[44:45]
	v_mov_b64_e32 v[44:45], v[42:43]
	v_cvt_pk_bf16_f32 v42, v50, v51
	v_cvt_pk_bf16_f32 v43, v48, v49
	v_add_co_u32_e32 v48, vcc, s13, v146
	v_cvt_pk_bf16_f32 v44, v44, v45
	v_cvt_pk_bf16_f32 v45, v52, v53
	v_lshl_add_u64 v[46:47], v[146:147], 0, s[24:25]
	s_nop 0
	v_addc_co_u32_e32 v49, vcc, 0, v147, vcc
	global_store_dwordx4 v[48:49], v[42:45], off sc1
	s_mov_b32 s13, 0x50000
	s_mov_b64 s[24:25], 0x50000
	v_mov_b64_e32 v[42:43], v[32:33]
	v_mov_b64_e32 v[32:33], v[30:31]
	v_cvt_pk_bf16_f32 v30, v38, v39
	v_cvt_pk_bf16_f32 v31, v40, v41
	s_nop 0
	v_cvt_pk_bf16_f32 v32, v32, v33
	v_cvt_pk_bf16_f32 v33, v42, v43
	global_store_dwordx4 v[46:47], v[30:33], off offset:256 sc1
	s_nop 1
	v_mov_b64_e32 v[32:33], v[36:37]
	v_mov_b64_e32 v[36:37], v[28:29]
	v_mov_b64_e32 v[28:29], v[26:27]
	v_cvt_pk_bf16_f32 v26, v34, v35
	v_cvt_pk_bf16_f32 v27, v32, v33
	v_add_co_u32_e32 v32, vcc, s13, v146
	v_cvt_pk_bf16_f32 v28, v28, v29
	v_cvt_pk_bf16_f32 v29, v36, v37
	v_lshl_add_u64 v[30:31], v[146:147], 0, s[24:25]
	s_nop 0
	v_addc_co_u32_e32 v33, vcc, 0, v147, vcc
	global_store_dwordx4 v[32:33], v[26:29], off sc1
	s_mov_b32 s13, 0x58000
	s_mov_b64 s[24:25], 0x58000
	v_mov_b64_e32 v[26:27], v[16:17]
	v_mov_b64_e32 v[16:17], v[14:15]
	v_cvt_pk_bf16_f32 v14, v22, v23
	v_cvt_pk_bf16_f32 v15, v24, v25
	s_nop 0
	v_cvt_pk_bf16_f32 v16, v16, v17
	v_cvt_pk_bf16_f32 v17, v26, v27
	global_store_dwordx4 v[30:31], v[14:17], off offset:256 sc1
	s_nop 1
	v_mov_b64_e32 v[16:17], v[20:21]
	v_mov_b64_e32 v[20:21], v[12:13]
	v_mov_b64_e32 v[12:13], v[10:11]
	v_cvt_pk_bf16_f32 v10, v18, v19
	v_cvt_pk_bf16_f32 v11, v16, v17
	v_add_co_u32_e32 v16, vcc, s13, v146
	v_lshl_add_u64 v[14:15], v[146:147], 0, s[24:25]
	s_nop 0
	v_addc_co_u32_e32 v17, vcc, 0, v147, vcc
	v_cvt_pk_bf16_f32 v12, v12, v13
	v_cvt_pk_bf16_f32 v13, v20, v21
	global_store_dwordx4 v[16:17], v[10:13], off sc1
	s_andn2_b64 vcc, exec, s[0:1]
	s_mov_b64 s[0:1], -1
	v_mov_b64_e32 v[10:11], v[4:5]
	v_mov_b64_e32 v[4:5], v[2:3]
	v_cvt_pk_bf16_f32 v2, v6, v7
	v_cvt_pk_bf16_f32 v3, v8, v9
	s_nop 0
	v_cvt_pk_bf16_f32 v4, v4, v5
	v_cvt_pk_bf16_f32 v5, v10, v11
	global_store_dwordx4 v[14:15], v[2:5], off offset:256 sc1
	s_cbranch_vccnz .LBB0_197
	s_andn2_b64 vcc, exec, s[6:7]
	s_cbranch_vccnz .LBB0_196
	s_barrier
	s_branch .LBB0_196

.LBB0_1001:
	s_ashr_i32 s19, s45, 31
	s_lshr_b32 s19, s19, 30
	s_add_i32 s19, s45, s19
	s_ashr_i32 s28, s19, 2
	s_ashr_i32 s29, s28, 31
	s_lshl_b32 s17, s45, 8
	s_lshl_b64 s[30:31], s[28:29], 25
	s_add_u32 s30, s36, s30
	s_addc_u32 s31, s37, s31
	s_lshl_b32 s19, s28, 10
	s_sub_i32 s17, s17, s19
	v_lshl_add_u32 v154, s24, 8, v148
	v_or_b32_e32 v146, s17, v150
	v_ashrrev_i32_e32 v147, 31, v146
	v_ashrrev_i32_e32 v155, 31, v154
	v_lshl_add_u64 v[156:157], v[146:147], 1, s[30:31]
	v_lshlrev_b64 v[146:147], 11, v[154:155]
	v_lshl_add_u64 v[146:147], v[156:157], 0, v[146:147]
	v_mov_b64_e32 v[158:159], v[124:125]
	v_mov_b64_e32 v[124:125], v[122:123]
	v_cvt_pk_bf16_f32 v122, v126, v127
	v_cvt_pk_bf16_f32 v123, v128, v129
	v_cvt_pk_bf16_f32 v124, v124, v125
	v_cvt_pk_bf16_f32 v125, v158, v159
	global_store_dwordx4 v[146:147], v[122:125], off sc1
	s_nop 1
	v_mov_b64_e32 v[122:123], v[112:113]
	v_mov_b64_e32 v[112:113], v[110:111]
	v_cvt_pk_bf16_f32 v110, v118, v119
	v_cvt_pk_bf16_f32 v111, v120, v121
	v_cvt_pk_bf16_f32 v112, v112, v113
	v_cvt_pk_bf16_f32 v113, v122, v123
	global_store_dwordx4 v[146:147], v[110:113], off offset:256 sc1
	s_nop 1
	v_or_b32_e32 v110, 16, v154
	v_ashrrev_i32_e32 v111, 31, v110
	v_lshlrev_b64 v[110:111], 11, v[110:111]
	v_lshl_add_u64 v[110:111], v[156:157], 0, v[110:111]
	v_mov_b64_e32 v[112:113], v[116:117]
	v_mov_b64_e32 v[116:117], v[108:109]
	v_mov_b64_e32 v[108:109], v[106:107]
	v_cvt_pk_bf16_f32 v106, v114, v115
	v_cvt_pk_bf16_f32 v107, v112, v113
	v_cvt_pk_bf16_f32 v108, v108, v109
	v_cvt_pk_bf16_f32 v109, v116, v117
	global_store_dwordx4 v[110:111], v[106:109], off sc1
	s_nop 1
	v_mov_b64_e32 v[106:107], v[96:97]
	v_mov_b64_e32 v[96:97], v[94:95]
	v_cvt_pk_bf16_f32 v94, v102, v103
	v_cvt_pk_bf16_f32 v95, v104, v105
	v_cvt_pk_bf16_f32 v96, v96, v97
	v_cvt_pk_bf16_f32 v97, v106, v107
	global_store_dwordx4 v[110:111], v[94:97], off offset:256 sc1
	s_nop 1
	v_or_b32_e32 v94, 32, v154
	v_ashrrev_i32_e32 v95, 31, v94
	v_lshlrev_b64 v[94:95], 11, v[94:95]
	v_lshl_add_u64 v[94:95], v[156:157], 0, v[94:95]
	v_mov_b64_e32 v[96:97], v[100:101]
	v_mov_b64_e32 v[100:101], v[92:93]
	v_mov_b64_e32 v[92:93], v[90:91]
	v_cvt_pk_bf16_f32 v90, v98, v99
	v_cvt_pk_bf16_f32 v91, v96, v97
	s_mov_b32 s17, 0x40000
	v_cvt_pk_bf16_f32 v92, v92, v93
	v_cvt_pk_bf16_f32 v93, v100, v101
	global_store_dwordx4 v[94:95], v[90:93], off sc1
	s_nop 1
	s_mov_b64 s[28:29], 0x40000
	v_mov_b64_e32 v[90:91], v[80:81]
	v_mov_b64_e32 v[80:81], v[78:79]
	v_cvt_pk_bf16_f32 v78, v86, v87
	v_cvt_pk_bf16_f32 v79, v88, v89
	v_cvt_pk_bf16_f32 v80, v80, v81
	v_cvt_pk_bf16_f32 v81, v90, v91
	global_store_dwordx4 v[94:95], v[78:81], off offset:256 sc1
	s_nop 1
	v_or_b32_e32 v78, 48, v154
	v_ashrrev_i32_e32 v79, 31, v78
	v_lshlrev_b64 v[78:79], 11, v[78:79]
	v_lshl_add_u64 v[78:79], v[156:157], 0, v[78:79]
	v_mov_b64_e32 v[80:81], v[84:85]
	v_mov_b64_e32 v[84:85], v[76:77]
	v_mov_b64_e32 v[76:77], v[74:75]
	v_cvt_pk_bf16_f32 v74, v82, v83
	v_cvt_pk_bf16_f32 v75, v80, v81
	v_cvt_pk_bf16_f32 v76, v76, v77
	v_cvt_pk_bf16_f32 v77, v84, v85
	global_store_dwordx4 v[78:79], v[74:77], off sc1
	s_nop 1
	v_mov_b64_e32 v[74:75], v[68:69]
	v_mov_b64_e32 v[68:69], v[66:67]
	v_cvt_pk_bf16_f32 v66, v70, v71
	v_cvt_pk_bf16_f32 v67, v72, v73
	v_cvt_pk_bf16_f32 v68, v68, v69
	v_cvt_pk_bf16_f32 v69, v74, v75
	global_store_dwordx4 v[78:79], v[66:69], off offset:256 sc1
	s_nop 1
	v_mov_b64_e32 v[68:69], v[60:61]
	v_mov_b64_e32 v[60:61], v[58:59]
	v_cvt_pk_bf16_f32 v58, v62, v63
	v_add_co_u32_e32 v62, vcc, s17, v146
	v_cvt_pk_bf16_f32 v59, v64, v65
	v_cvt_pk_bf16_f32 v60, v60, v61
	v_cvt_pk_bf16_f32 v61, v68, v69
	v_lshl_add_u64 v[66:67], v[146:147], 0, s[28:29]
	s_nop 0
	v_addc_co_u32_e32 v63, vcc, 0, v147, vcc
	global_store_dwordx4 v[62:63], v[58:61], off sc1
	s_mov_b32 s17, 0x48000
	s_mov_b64 s[28:29], 0x48000
	v_mov_b64_e32 v[58:59], v[48:49]
	v_mov_b64_e32 v[48:49], v[46:47]
	v_cvt_pk_bf16_f32 v46, v54, v55
	v_cvt_pk_bf16_f32 v47, v56, v57
	v_cvt_pk_bf16_f32 v48, v48, v49
	v_cvt_pk_bf16_f32 v49, v58, v59
	global_store_dwordx4 v[66:67], v[46:49], off offset:256 sc1
	s_nop 1
	s_nop 0
	v_mov_b64_e32 v[48:49], v[52:53]
	v_mov_b64_e32 v[52:53], v[44:45]
	v_mov_b64_e32 v[44:45], v[42:43]
	v_cvt_pk_bf16_f32 v42, v50, v51
	v_cvt_pk_bf16_f32 v43, v48, v49
	v_add_co_u32_e32 v48, vcc, s17, v146
	v_cvt_pk_bf16_f32 v44, v44, v45
	v_cvt_pk_bf16_f32 v45, v52, v53
	v_lshl_add_u64 v[46:47], v[146:147], 0, s[28:29]
	s_nop 0
	v_addc_co_u32_e32 v49, vcc, 0, v147, vcc
	global_store_dwordx4 v[48:49], v[42:45], off sc1
	s_mov_b32 s17, 0x50000
	s_mov_b64 s[28:29], 0x50000
	v_mov_b64_e32 v[42:43], v[32:33]
	v_mov_b64_e32 v[32:33], v[30:31]
	v_cvt_pk_bf16_f32 v30, v38, v39
	v_cvt_pk_bf16_f32 v31, v40, v41
	s_nop 0
	v_cvt_pk_bf16_f32 v32, v32, v33
	v_cvt_pk_bf16_f32 v33, v42, v43
	global_store_dwordx4 v[46:47], v[30:33], off offset:256 sc1
	s_nop 1
	v_mov_b64_e32 v[32:33], v[36:37]
	v_mov_b64_e32 v[36:37], v[28:29]
	v_mov_b64_e32 v[28:29], v[26:27]
	v_cvt_pk_bf16_f32 v26, v34, v35
	v_cvt_pk_bf16_f32 v27, v32, v33
	v_add_co_u32_e32 v32, vcc, s17, v146
	v_cvt_pk_bf16_f32 v28, v28, v29
	v_cvt_pk_bf16_f32 v29, v36, v37
	v_lshl_add_u64 v[30:31], v[146:147], 0, s[28:29]
	s_nop 0
	v_addc_co_u32_e32 v33, vcc, 0, v147, vcc
	global_store_dwordx4 v[32:33], v[26:29], off sc1
	s_mov_b32 s17, 0x58000
	s_mov_b64 s[28:29], 0x58000
	v_mov_b64_e32 v[26:27], v[16:17]
	v_mov_b64_e32 v[16:17], v[14:15]
	v_cvt_pk_bf16_f32 v14, v22, v23
	v_cvt_pk_bf16_f32 v15, v24, v25
	s_nop 0
	v_cvt_pk_bf16_f32 v16, v16, v17
	v_cvt_pk_bf16_f32 v17, v26, v27
	global_store_dwordx4 v[30:31], v[14:17], off offset:256 sc1
	s_nop 1
	v_mov_b64_e32 v[16:17], v[20:21]
	v_mov_b64_e32 v[20:21], v[12:13]
	v_mov_b64_e32 v[12:13], v[10:11]
	v_cvt_pk_bf16_f32 v10, v18, v19
	v_cvt_pk_bf16_f32 v11, v16, v17
	v_add_co_u32_e32 v16, vcc, s17, v146
	v_lshl_add_u64 v[14:15], v[146:147], 0, s[28:29]
	s_nop 0
	v_addc_co_u32_e32 v17, vcc, 0, v147, vcc
	v_cvt_pk_bf16_f32 v12, v12, v13
	v_cvt_pk_bf16_f32 v13, v20, v21
	global_store_dwordx4 v[16:17], v[10:13], off sc1
	s_andn2_b64 vcc, exec, s[0:1]
	s_mov_b64 s[0:1], -1
	v_mov_b64_e32 v[10:11], v[4:5]
	v_mov_b64_e32 v[4:5], v[2:3]
	v_cvt_pk_bf16_f32 v2, v6, v7
	v_cvt_pk_bf16_f32 v3, v8, v9
	s_nop 0
	v_cvt_pk_bf16_f32 v4, v4, v5
	v_cvt_pk_bf16_f32 v5, v10, v11
	global_store_dwordx4 v[14:15], v[2:5], off offset:256 sc1
	s_cbranch_vccnz .LBB0_994
	s_andn2_b64 vcc, exec, s[8:9]
	s_cbranch_vccnz .LBB0_993
	s_barrier
	s_branch .LBB0_993
